# block->tile rotation for the back-to-back small GEMMs (IN+VS, LR+QB+KN+KV) so their extra tiles land on different blocks
# speedup vs baseline: 1.0533x; 1.0078x over previous
;     DI bool next(int i, Unit& u) const {
;         const long L = (long)i * G + c; if (L >= nwg) return false;
;         int wgid = (int)L; { const int q = nwg / NXCD, r = nwg % NXCD, xcd = wgid % NXCD, off = wgid / NXCD; wgid = (xcd < r ? xcd * (q + 1) : r * (q + 1) + (xcd - r) * q) + off; }
;         const int nig = WGM * nN, gid = wgid / nig, fm = gid * WGM, gsz = (nM - fm) < WGM ? (nM - fm) : WGM;
;         u.pm = fm + ((wgid % nig) % gsz); u.pn = (wgid % nig) / gsz; return true;
;     }
; template <class Epi> DI void run_gemm(int wv, LAS unsigned char* lds, const bf16_t* A, const bf16_t* Bt, int M, int N, int K, const Epi& E) {
;     pg8::Gemm g{A, Bt, M, N, K}; pg8::StaticOrder S; S.init(M, N, (int)gridDim.x, (int)blockIdx.x);
;     pg8::gemm_phase<Epi>(wv, lds, g, S, E);
.LBB0_488:
	v_mov_b32_e32 v8, v254
	s_add_u32 s100, s2, 160
	s_and_b32 s100, s100, 0xff
	s_mov_b32 s101, 0
	s_cmpk_lt_i32 s100, 0x143
	v_add_u32_e32 v0, s33, v8
	s_cselect_b64 s[6:7], -1, 0
	s_cmpk_gt_i32 s100, 0x142
	v_readfirstlane_b32 s10, v0
	s_cbranch_scc1 .LBB0_494
	s_lshr_b32 s4, s3, 29
	s_add_i32 s8, s100, s4
	s_and_b32 s4, s8, -8
	s_sub_i32 s9, s100, s4
	s_cmp_gt_i32 s9, 2
	s_cbranch_scc0 .LBB0_491
	s_mul_i32 s4, s9, 40
	s_or_b32 s11, s4, 3
	s_cbranch_execz .LBB0_492
	s_branch .LBB0_493

;     DI bool next(int i, Unit& u) const {
;         const long L = (long)i * G + c; if (L >= nwg) return false;
;         int wgid = (int)L; { const int q = nwg / NXCD, r = nwg % NXCD, xcd = wgid % NXCD, off = wgid / NXCD; wgid = (xcd < r ? xcd * (q + 1) : r * (q + 1) + (xcd - r) * q) + off; }
;         const int nig = WGM * nN, gid = wgid / nig, fm = gid * WGM, gsz = (nM - fm) < WGM ? (nM - fm) : WGM;
;         u.pm = fm + ((wgid % nig) % gsz); u.pn = (wgid % nig) / gsz; return true;
;     }
; template <class Epi>
; DI void gemm_phase(int wv, LAS unsigned char* lds, const Gemm g, const StaticOrder& S, const Epi& E) {
;     ...
;         const bool has_next = S.next(ui + 1, nxt);
;         const char* nA = has_next ? (const char*)g.A + (size_t)nxt.pm * tstep : cA; const char* nB = has_next ? (const char*)g.Bt + (size_t)nxt.pn * tstep : cB;
.LBB0_499:
	s_add_i32 s59, s59, 1
	s_mul_i32 s6, s59, s45
	s_mul_hi_u32 s7, s59, s44
	s_add_i32 s7, s7, s6
	s_mul_i32 s6, s59, s44
	s_add_u32 s36, s6, s100
	s_addc_u32 s37, s7, s3
	v_cmp_gt_i64_e64 s[6:7], s[36:37], v[144:145]
	s_and_b64 vcc, exec, s[6:7]
	s_cbranch_vccnz .LBB0_505
	s_ashr_i32 s9, s36, 31
	s_lshr_b32 s9, s9, 29
	s_add_i32 s9, s36, s9
	s_and_b32 s28, s9, -8
	s_sub_i32 s30, s36, s28
	s_cmp_gt_i32 s30, 2
	s_mov_b64 s[28:29], -1
	s_cbranch_scc0 .LBB0_502
	s_mul_i32 s28, s30, 40
	s_or_b32 s31, s28, 3
	s_mov_b64 s[28:29], 0

;     DI bool next(int i, Unit& u) const {
;         const long L = (long)i * G + c; if (L >= nwg) return false;
;         int wgid = (int)L; { const int q = nwg / NXCD, r = nwg % NXCD, xcd = wgid % NXCD, off = wgid / NXCD; wgid = (xcd < r ? xcd * (q + 1) : r * (q + 1) + (xcd - r) * q) + off; }
;         const int nig = WGM * nN, gid = wgid / nig, fm = gid * WGM, gsz = (nM - fm) < WGM ? (nM - fm) : WGM;
;         u.pm = fm + ((wgid % nig) % gsz); u.pn = (wgid % nig) / gsz; return true;
;     }
; template <class Epi> DI void run_gemm(int wv, LAS unsigned char* lds, const bf16_t* A, const bf16_t* Bt, int M, int N, int K, const Epi& E) {
;     pg8::Gemm g{A, Bt, M, N, K}; pg8::StaticOrder S; S.init(M, N, (int)gridDim.x, (int)blockIdx.x);
;     pg8::gemm_phase<Epi>(wv, lds, g, S, E);
.LBB0_686:
	v_mov_b32_e32 v8, v254
	s_add_u32 s100, s2, 176
	s_and_b32 s100, s100, 0xff
	s_mov_b32 s101, 0
	s_cmpk_lt_i32 s100, 0x286
	v_add_u32_e32 v0, s33, v8
	s_cselect_b64 s[14:15], -1, 0
	s_cmpk_gt_i32 s100, 0x285
	v_readfirstlane_b32 s10, v0
	s_cbranch_scc1 .LBB0_692
	s_lshr_b32 s8, s3, 29
	s_add_i32 s11, s100, s8
	s_and_b32 s8, s11, -8
	s_sub_i32 s12, s100, s8
	s_cmp_gt_i32 s12, 5
	s_cbranch_scc0 .LBB0_689
	s_mul_i32 s8, s12, 0x50
	s_or_b32 s13, s8, 6
	s_cbranch_execz .LBB0_690
	s_branch .LBB0_691

;     DI bool next(int i, Unit& u) const {
;         const long L = (long)i * G + c; if (L >= nwg) return false;
;         int wgid = (int)L; { const int q = nwg / NXCD, r = nwg % NXCD, xcd = wgid % NXCD, off = wgid / NXCD; wgid = (xcd < r ? xcd * (q + 1) : r * (q + 1) + (xcd - r) * q) + off; }
;         const int nig = WGM * nN, gid = wgid / nig, fm = gid * WGM, gsz = (nM - fm) < WGM ? (nM - fm) : WGM;
;         u.pm = fm + ((wgid % nig) % gsz); u.pn = (wgid % nig) / gsz; return true;
;     }
; template <class Epi>
; DI void gemm_phase(int wv, LAS unsigned char* lds, const Gemm g, const StaticOrder& S, const Epi& E) {
;     ...
;         const bool has_next = S.next(ui + 1, nxt);
;         const char* nA = has_next ? (const char*)g.A + (size_t)nxt.pm * tstep : cA; const char* nB = has_next ? (const char*)g.Bt + (size_t)nxt.pn * tstep : cB;
.LBB0_697:
	s_add_i32 s55, s55, 1
	s_mul_i32 s6, s55, s45
	s_mul_hi_u32 s7, s55, s44
	s_add_i32 s7, s7, s6
	s_mul_i32 s6, s55, s44
	s_add_u32 s28, s6, s100
	s_addc_u32 s29, s7, s3
	v_cmp_gt_i64_e64 s[6:7], s[28:29], v[140:141]
	s_and_b64 vcc, exec, s[6:7]
	s_cbranch_vccnz .LBB0_703
	s_ashr_i32 s13, s28, 31
	s_lshr_b32 s13, s13, 29
	s_add_i32 s13, s28, s13
	s_and_b32 s18, s13, -8
	s_sub_i32 s20, s28, s18
	s_cmp_gt_i32 s20, 5
	s_mov_b64 s[18:19], -1
	s_cbranch_scc0 .LBB0_700
	s_mul_i32 s18, s20, 0x50
	s_or_b32 s21, s18, 6
	s_mov_b64 s[18:19], 0

;     DI bool next(int i, Unit& u) const {
;         const long L = (long)i * G + c; if (L >= nwg) return false;
;         int wgid = (int)L; { const int q = nwg / NXCD, r = nwg % NXCD, xcd = wgid % NXCD, off = wgid / NXCD; wgid = (xcd < r ? xcd * (q + 1) : r * (q + 1) + (xcd - r) * q) + off; }
;         const int nig = WGM * nN, gid = wgid / nig, fm = gid * WGM, gsz = (nM - fm) < WGM ? (nM - fm) : WGM;
;         u.pm = fm + ((wgid % nig) % gsz); u.pn = (wgid % nig) / gsz; return true;
;     }
.LBB0_740:
	v_mov_b32_e32 v8, v254
	s_and_b64 vcc, exec, s[4:5]
	v_add_u32_e32 v0, s33, v8
	s_nop 0
	v_readfirstlane_b32 s10, v0
	s_cbranch_vccnz .LBB0_746
	s_lshr_b32 s8, s3, 29
	s_add_u32 s100, s2, 40
	s_and_b32 s100, s100, 0xff
	s_mov_b32 s101, 0
	s_add_i32 s8, s100, s8
	s_and_b32 s9, s8, -8
	s_sub_i32 s9, s100, s9
	s_cmp_gt_i32 s9, 2
	s_cbranch_scc0 .LBB0_743
	s_mul_i32 s11, s9, 40
	s_or_b32 s11, s11, 3
	s_cbranch_execz .LBB0_744
	s_branch .LBB0_745

; #define PG8_STAGE(bufoff, gbase, voff) do { _Pragma("unroll") for (int _i = 0; _i < 2; ++_i) \
;         __builtin_amdgcn_global_load_lds((const unsigned*)((const char*)(gbase) + (voff)[_i]), (LAS unsigned*)(lds + (bufoff) + ldsw + _i * 8192), 16, 0, 0); } while (0)
; #define PG8_WAIT_V(n) asm volatile("s_waitcnt vmcnt(" #n ")" ::: "memory")
; #define PG8_BAR __builtin_amdgcn_s_barrier()
; template <class Epi>
; DI void gemm_phase(int wv, LAS unsigned char* lds, const Gemm g, const StaticOrder& S, const Epi& E) {
;     ...
;     for (int i = 0; i < 2; ++i) { int R, C; stage_rc(tid * 16 + i * 8192, R, C); const int Rb = Epi::PERM ? ((R & ~31) + perm32(R & 31)) : R; voffA[i] = (unsigned)(R * K + C) * 2u; voffB[i] = (unsigned)(Rb * K + C) * 2u; }
;     const size_t kstep = (size_t)(BK * 2);
;     const size_t hstep = (size_t)HALF * K * 2;
;     const size_t tstep = 2 * hstep;
;     const unsigned ldsw = (unsigned)wid * 1024u;
;     const int aoff = lds_byte(wr * 64 + fr, fq * 8), boff = lds_byte(wc * 32 + fr, fq * 8);
;     ...
;     Unit cur, nxt; int ui = 0;
;     if (!S.next(0, cur)) return;
;     f32x4 acc[2][2][4][2];
; #pragma unroll
;     for (int a = 0; a < 2; ++a)
; #pragma unroll
;         for (int b = 0; b < 2; ++b)
; #pragma unroll
;             for (int m = 0; m < 4; ++m)
; #pragma unroll
;                 for (int n = 0; n < 2; ++n) acc[a][b][m][n] = (f32x4){0.f, 0.f, 0.f, 0.f};
;     bf16x8 At[4][2], B0[2][2], B1[2][2];
;     const char* cA = (const char*)g.A + (size_t)cur.pm * tstep; const char* cB = (const char*)g.Bt + (size_t)cur.pn * tstep;
;     PG8_STAGE(PG8_SB(0, 0), cB, voffB); PG8_STAGE(PG8_SA(0, 0), cA, voffA); PG8_STAGE(PG8_SB(0, 1), cB + hstep, voffB); PG8_STAGE(PG8_SA(0, 1), cA + hstep, voffA);
;     if (wr == 1) PG8_BAR;
;     PG8_WAIT_V(4); PG8_BAR;
;     PG8_STAGE(PG8_SB(1, 0), cB + kstep, voffB); PG8_STAGE(PG8_SA(1, 0), cA + kstep, voffA); PG8_STAGE(PG8_SB(1, 1), cB + hstep + kstep, voffB);
;     PG8_WAIT_V(6); PG8_BAR;
;     for (;;) {
;         const bool has_next = S.next(ui + 1, nxt);
;         const char* nA = has_next ? (const char*)g.A + (size_t)nxt.pm * tstep : cA; const char* nB = has_next ? (const char*)g.Bt + (size_t)nxt.pn * tstep : cB;
.LBB0_749:
	s_waitcnt lgkmcnt(0)
	s_add_u32 s14, s6, 0x29bb8000
	s_addc_u32 s15, s7, 0
	s_lshl_b32 s13, s16, 6
	s_lshl_b32 s18, s16, 13
	s_lshl_b32 s6, s17, 5
	s_mov_b64 s[16:17], 0x80
	s_and_b32 s55, s6, 0x60
	s_add_i32 m0, s51, 0x18000
	v_lshl_add_u64 v[6:7], v[6:7], 0, s[16:17]
	s_lshl_b32 s19, s55, 7
	s_waitcnt vmcnt(4)
	s_barrier
	global_load_lds_dwordx4 v[6:7], off
	v_lshl_add_u64 v[4:5], v[4:5], 0, s[16:17]
	s_add_i32 m0, s51, 0x1a000
	s_add_i32 s58, s51, 0x8000
	s_add_i32 s59, s51, 0xa000
	global_load_lds_dwordx4 v[4:5], off
	v_lshl_add_u64 v[2:3], v[2:3], 0, s[16:17]
	s_mov_b32 m0, s58
	s_add_u32 s6, s68, 0x10080
	global_load_lds_dwordx4 v[2:3], off
	v_lshl_add_u64 v[0:1], v[0:1], 0, s[16:17]
	s_mov_b32 m0, s59
	s_addc_u32 s7, s69, 0
	global_load_lds_dwordx4 v[0:1], off
	s_add_i32 m0, s51, 0x1c000
	v_lshl_add_u64 v[0:1], s[6:7], 0, v[130:131]
	global_load_lds_dwordx4 v[0:1], off
	v_lshl_add_u64 v[0:1], s[6:7], 0, v[134:135]
	s_add_i32 m0, s51, 0x1e000
	v_lshlrev_b32_e32 v2, 2, v8
	global_load_lds_dwordx4 v[0:1], off
	v_lshrrev_b32_e32 v1, 1, v8
	v_and_b32_e32 v144, 24, v1
	v_and_b32_e32 v0, 15, v8
	v_lshlrev_b32_e32 v1, 1, v144
	v_lshl_or_b32 v1, v0, 6, v1
	v_and_b32_e32 v2, 32, v2
	s_waitcnt vmcnt(6)
	v_bitop3_b32 v3, v1, s18, v2 bitop3:0xde
	v_bitop3_b32 v145, v1, s19, v2 bitop3:0xde
	s_ashr_i32 s6, s13, 31
	s_add_i32 s61, 0, 0x10000
	s_add_i32 s76, 0, 0x14000
	v_or_b32_e32 v136, s13, v0
	v_mov_b32_e32 v137, s6
	s_add_i32 s60, s100, s44
	v_mov_b64_e32 v[140:141], 0x142
	v_add_u32_e32 v146, s61, v145
	v_add_u32_e32 v147, 0, v3
	s_add_i32 s74, s51, 0xc000
	s_add_i32 s75, s51, 0xe000
	v_add_u32_e32 v148, s76, v145
	s_mov_b64 s[18:19], 0x100
	s_mov_b64 s[20:21], 0x180
	s_movk_i32 s77, 0x100
	s_movk_i32 s78, 0x300
	s_mov_b64 s[28:29], 0xb0
	s_mov_b64 s[30:31], s[100:101]
	s_barrier
	s_branch .LBB0_751

;     DI bool next(int i, Unit& u) const {
;         const long L = (long)i * G + c; if (L >= nwg) return false;
;         int wgid = (int)L; { const int q = nwg / NXCD, r = nwg % NXCD, xcd = wgid % NXCD, off = wgid / NXCD; wgid = (xcd < r ? xcd * (q + 1) : r * (q + 1) + (xcd - r) * q) + off; }
;         const int nig = WGM * nN, gid = wgid / nig, fm = gid * WGM, gsz = (nM - fm) < WGM ? (nM - fm) : WGM;
;         u.pm = fm + ((wgid % nig) % gsz); u.pn = (wgid % nig) / gsz; return true;
;     }
.LBB0_792:
	v_mov_b32_e32 v8, v254
	s_and_b64 vcc, exec, s[4:5]
	v_add_u32_e32 v0, s33, v8
	s_nop 0
	v_readfirstlane_b32 s10, v0
	s_cbranch_vccnz .LBB0_798
	s_lshr_b32 s11, s3, 29
	s_add_u32 s100, s2, 224
	s_and_b32 s100, s100, 0xff
	s_mov_b32 s101, 0
	s_add_i32 s11, s100, s11
	s_and_b32 s12, s11, -8
	s_sub_i32 s14, s100, s12
	s_cmp_gt_i32 s14, 2
	s_cbranch_scc0 .LBB0_795
	s_mul_i32 s12, s14, 40
	s_or_b32 s15, s12, 3
	s_cbranch_execz .LBB0_796
	s_branch .LBB0_797

;     DI bool next(int i, Unit& u) const {
;         const long L = (long)i * G + c; if (L >= nwg) return false;
;         int wgid = (int)L; { const int q = nwg / NXCD, r = nwg % NXCD, xcd = wgid % NXCD, off = wgid / NXCD; wgid = (xcd < r ? xcd * (q + 1) : r * (q + 1) + (xcd - r) * q) + off; }
;         const int nig = WGM * nN, gid = wgid / nig, fm = gid * WGM, gsz = (nM - fm) < WGM ? (nM - fm) : WGM;
;         u.pm = fm + ((wgid % nig) % gsz); u.pn = (wgid % nig) / gsz; return true;
;     }
; template <class Epi>
; DI void gemm_phase(int wv, LAS unsigned char* lds, const Gemm g, const StaticOrder& S, const Epi& E) {
;     ...
;         const bool has_next = S.next(ui + 1, nxt);
;         const char* nA = has_next ? (const char*)g.A + (size_t)nxt.pm * tstep : cA; const char* nB = has_next ? (const char*)g.Bt + (size_t)nxt.pn * tstep : cB;
.LBB0_803:
	s_add_i32 s55, s55, 1
	s_mul_i32 s6, s55, s45
	s_mul_hi_u32 s7, s55, s44
	s_add_i32 s7, s7, s6
	s_mul_i32 s6, s55, s44
	s_add_u32 s28, s6, s100
	s_addc_u32 s29, s7, s3
	v_cmp_gt_i64_e64 s[6:7], s[28:29], v[140:141]
	s_and_b64 vcc, exec, s[6:7]
	s_cbranch_vccnz .LBB0_809
	s_ashr_i32 s13, s28, 31
	s_lshr_b32 s13, s13, 29
	s_add_i32 s13, s28, s13
	s_and_b32 s18, s13, -8
	s_sub_i32 s20, s28, s18
	s_cmp_gt_i32 s20, 2
	s_mov_b64 s[18:19], -1
	s_cbranch_scc0 .LBB0_806
	s_mul_i32 s18, s20, 40
	s_or_b32 s21, s18, 3
	s_mov_b64 s[18:19], 0

;     DI bool next(int i, Unit& u) const {
;         const long L = (long)i * G + c; if (L >= nwg) return false;
;         int wgid = (int)L; { const int q = nwg / NXCD, r = nwg % NXCD, xcd = wgid % NXCD, off = wgid / NXCD; wgid = (xcd < r ? xcd * (q + 1) : r * (q + 1) + (xcd - r) * q) + off; }
;         const int nig = WGM * nN, gid = wgid / nig, fm = gid * WGM, gsz = (nM - fm) < WGM ? (nM - fm) : WGM;
;         u.pm = fm + ((wgid % nig) % gsz); u.pn = (wgid % nig) / gsz; return true;
;     }
; template <class Epi> DI void run_gemm(int wv, LAS unsigned char* lds, const bf16_t* A, const bf16_t* Bt, int M, int N, int K, const Epi& E) {
;     pg8::Gemm g{A, Bt, M, N, K}; pg8::StaticOrder S; S.init(M, N, (int)gridDim.x, (int)blockIdx.x);
;     pg8::gemm_phase<Epi>(wv, lds, g, S, E);
.LBB0_2122:
	v_mov_b32_e32 v8, v254
	s_and_b64 vcc, exec, s[4:5]
	v_add_u32_e32 v0, s33, v8
	s_nop 0
	v_readfirstlane_b32 s8, v0
	s_cbranch_vccnz .LBB0_2128
	s_lshr_b32 s9, s3, 29
	s_add_u32 s100, s2, 160
	s_and_b32 s100, s100, 0xff
	s_mov_b32 s101, 0
	s_add_i32 s9, s100, s9
	s_and_b32 s10, s9, -8
	s_sub_i32 s14, s100, s10
	s_cmp_gt_i32 s14, 2
	s_cbranch_scc0 .LBB0_2125
	s_mul_i32 s10, s14, 40
	s_or_b32 s15, s10, 3
	s_cbranch_execz .LBB0_2126
	s_branch .LBB0_2127

;     DI bool next(int i, Unit& u) const {
;         const long L = (long)i * G + c; if (L >= nwg) return false;
;         int wgid = (int)L; { const int q = nwg / NXCD, r = nwg % NXCD, xcd = wgid % NXCD, off = wgid / NXCD; wgid = (xcd < r ? xcd * (q + 1) : r * (q + 1) + (xcd - r) * q) + off; }
;         const int nig = WGM * nN, gid = wgid / nig, fm = gid * WGM, gsz = (nM - fm) < WGM ? (nM - fm) : WGM;
;         u.pm = fm + ((wgid % nig) % gsz); u.pn = (wgid % nig) / gsz; return true;
;     }
; template <class Epi>
; DI void gemm_phase(int wv, LAS unsigned char* lds, const Gemm g, const StaticOrder& S, const Epi& E) {
;     ...
;         const bool has_next = S.next(ui + 1, nxt);
;         const char* nA = has_next ? (const char*)g.A + (size_t)nxt.pm * tstep : cA; const char* nB = has_next ? (const char*)g.Bt + (size_t)nxt.pn * tstep : cB;
.LBB0_2133:
	s_add_i32 s69, s69, 1
	s_mul_i32 s10, s69, s45
	s_mul_hi_u32 s11, s69, s44
	s_add_i32 s11, s11, s10
	s_mul_i32 s10, s69, s44
	s_add_u32 s54, s10, s100
	s_addc_u32 s55, s11, s3
	v_cmp_gt_i64_e64 s[10:11], s[54:55], v[144:145]
	s_and_b64 vcc, exec, s[10:11]
	s_cbranch_vccnz .LBB0_2139
	s_ashr_i32 s15, s54, 31
	s_lshr_b32 s15, s15, 29
	s_add_i32 s15, s54, s15
	s_and_b32 s30, s15, -8
	s_sub_i32 s52, s54, s30
	s_cmp_gt_i32 s52, 2
	s_mov_b64 s[30:31], -1
	s_cbranch_scc0 .LBB0_2136
	s_mul_i32 s30, s52, 40
	s_or_b32 s53, s30, 3
	s_mov_b64 s[30:31], 0

;     DI bool next(int i, Unit& u) const {
;         const long L = (long)i * G + c; if (L >= nwg) return false;
;         int wgid = (int)L; { const int q = nwg / NXCD, r = nwg % NXCD, xcd = wgid % NXCD, off = wgid / NXCD; wgid = (xcd < r ? xcd * (q + 1) : r * (q + 1) + (xcd - r) * q) + off; }
;         const int nig = WGM * nN, gid = wgid / nig, fm = gid * WGM, gsz = (nM - fm) < WGM ? (nM - fm) : WGM;
;         u.pm = fm + ((wgid % nig) % gsz); u.pn = (wgid % nig) / gsz; return true;
;     }
; template <class Epi> DI void run_gemm(int wv, LAS unsigned char* lds, const bf16_t* A, const bf16_t* Bt, int M, int N, int K, const Epi& E) {
;     pg8::Gemm g{A, Bt, M, N, K}; pg8::StaticOrder S; S.init(M, N, (int)gridDim.x, (int)blockIdx.x);
;     pg8::gemm_phase<Epi>(wv, lds, g, S, E);
.LBB0_2320:
	v_mov_b32_e32 v8, v254
	v_readlane_b32 s8, v255, 13
	v_readlane_b32 s9, v255, 14
	v_add_u32_e32 v0, s33, v8
	s_and_b64 vcc, exec, s[8:9]
	v_readfirstlane_b32 s41, v0
	s_cbranch_vccnz .LBB0_2326
	s_lshr_b32 s8, s3, 29
	s_add_u32 s100, s2, 176
	s_and_b32 s100, s100, 0xff
	s_mov_b32 s101, 0
	s_add_i32 s8, s100, s8
	s_and_b32 s9, s8, -8
	s_sub_i32 s9, s100, s9
	s_cmp_gt_i32 s9, 5
	s_cbranch_scc0 .LBB0_2323
	s_mul_i32 s10, s9, 0x50
	s_or_b32 s16, s10, 6
	s_cbranch_execz .LBB0_2324
	s_branch .LBB0_2325

;     DI bool next(int i, Unit& u) const {
;         const long L = (long)i * G + c; if (L >= nwg) return false;
;         int wgid = (int)L; { const int q = nwg / NXCD, r = nwg % NXCD, xcd = wgid % NXCD, off = wgid / NXCD; wgid = (xcd < r ? xcd * (q + 1) : r * (q + 1) + (xcd - r) * q) + off; }
;         const int nig = WGM * nN, gid = wgid / nig, fm = gid * WGM, gsz = (nM - fm) < WGM ? (nM - fm) : WGM;
;         u.pm = fm + ((wgid % nig) % gsz); u.pn = (wgid % nig) / gsz; return true;
;     }
; template <class Epi>
; DI void gemm_phase(int wv, LAS unsigned char* lds, const Gemm g, const StaticOrder& S, const Epi& E) {
;     ...
;         const bool has_next = S.next(ui + 1, nxt);
;         const char* nA = has_next ? (const char*)g.A + (size_t)nxt.pm * tstep : cA; const char* nB = has_next ? (const char*)g.Bt + (size_t)nxt.pn * tstep : cB;
.LBB0_2331:
	s_add_i32 s79, s79, 1
	s_mul_i32 s8, s79, s45
	s_mul_hi_u32 s9, s79, s44
	s_add_i32 s9, s9, s8
	s_mul_i32 s8, s79, s44
	s_add_u32 s30, s8, s100
	s_addc_u32 s31, s9, s3
	v_cmp_gt_i64_e64 s[8:9], s[30:31], v[140:141]
	s_and_b64 vcc, exec, s[8:9]
	s_cbranch_vccnz .LBB0_2337
	s_ashr_i32 s11, s30, 31
	s_lshr_b32 s11, s11, 29
	s_add_i32 s11, s30, s11
	s_and_b32 s26, s11, -8
	s_sub_i32 s28, s30, s26
	s_cmp_gt_i32 s28, 5
	s_mov_b64 s[26:27], -1
	s_cbranch_scc0 .LBB0_2334
	s_mul_i32 s26, s28, 0x50
	s_or_b32 s29, s26, 6
	s_mov_b64 s[26:27], 0

;     DI bool next(int i, Unit& u) const {
;         const long L = (long)i * G + c; if (L >= nwg) return false;
;         int wgid = (int)L; { const int q = nwg / NXCD, r = nwg % NXCD, xcd = wgid % NXCD, off = wgid / NXCD; wgid = (xcd < r ? xcd * (q + 1) : r * (q + 1) + (xcd - r) * q) + off; }
;         const int nig = WGM * nN, gid = wgid / nig, fm = gid * WGM, gsz = (nM - fm) < WGM ? (nM - fm) : WGM;
;         u.pm = fm + ((wgid % nig) % gsz); u.pn = (wgid % nig) / gsz; return true;
;     }
.LBB0_2374:
	v_mov_b32_e32 v8, v254
	s_and_b64 vcc, exec, s[4:5]
	v_add_u32_e32 v0, s33, v8
	s_nop 0
	v_readfirstlane_b32 s68, v0
	s_cbranch_vccnz .LBB0_2380
	s_lshr_b32 s8, s3, 29
	s_add_u32 s100, s2, 40
	s_and_b32 s100, s100, 0xff
	s_mov_b32 s101, 0
	s_add_i32 s10, s100, s8
	s_and_b32 s8, s10, -8
	s_sub_i32 s11, s100, s8
	s_cmp_gt_i32 s11, 2
	s_cbranch_scc0 .LBB0_2377
	s_mul_i32 s8, s11, 40
	s_or_b32 s16, s8, 3
	s_cbranch_execz .LBB0_2378
	s_branch .LBB0_2379

; #define PG8_STAGE(bufoff, gbase, voff) do { _Pragma("unroll") for (int _i = 0; _i < 2; ++_i) \
;         __builtin_amdgcn_global_load_lds((const unsigned*)((const char*)(gbase) + (voff)[_i]), (LAS unsigned*)(lds + (bufoff) + ldsw + _i * 8192), 16, 0, 0); } while (0)
; #define PG8_WAIT_V(n) asm volatile("s_waitcnt vmcnt(" #n ")" ::: "memory")
; #define PG8_BAR __builtin_amdgcn_s_barrier()
; template <class Epi>
; DI void gemm_phase(int wv, LAS unsigned char* lds, const Gemm g, const StaticOrder& S, const Epi& E) {
;     ...
;     for (int i = 0; i < 2; ++i) { int R, C; stage_rc(tid * 16 + i * 8192, R, C); const int Rb = Epi::PERM ? ((R & ~31) + perm32(R & 31)) : R; voffA[i] = (unsigned)(R * K + C) * 2u; voffB[i] = (unsigned)(Rb * K + C) * 2u; }
;     const size_t kstep = (size_t)(BK * 2);
;     const size_t hstep = (size_t)HALF * K * 2;
;     const size_t tstep = 2 * hstep;
;     const unsigned ldsw = (unsigned)wid * 1024u;
;     const int aoff = lds_byte(wr * 64 + fr, fq * 8), boff = lds_byte(wc * 32 + fr, fq * 8);
;     ...
;     Unit cur, nxt; int ui = 0;
;     if (!S.next(0, cur)) return;
;     f32x4 acc[2][2][4][2];
; #pragma unroll
;     for (int a = 0; a < 2; ++a)
; #pragma unroll
;         for (int b = 0; b < 2; ++b)
; #pragma unroll
;             for (int m = 0; m < 4; ++m)
; #pragma unroll
;                 for (int n = 0; n < 2; ++n) acc[a][b][m][n] = (f32x4){0.f, 0.f, 0.f, 0.f};
;     bf16x8 At[4][2], B0[2][2], B1[2][2];
;     const char* cA = (const char*)g.A + (size_t)cur.pm * tstep; const char* cB = (const char*)g.Bt + (size_t)cur.pn * tstep;
;     PG8_STAGE(PG8_SB(0, 0), cB, voffB); PG8_STAGE(PG8_SA(0, 0), cA, voffA); PG8_STAGE(PG8_SB(0, 1), cB + hstep, voffB); PG8_STAGE(PG8_SA(0, 1), cA + hstep, voffA);
;     if (wr == 1) PG8_BAR;
;     PG8_WAIT_V(4); PG8_BAR;
;     PG8_STAGE(PG8_SB(1, 0), cB + kstep, voffB); PG8_STAGE(PG8_SA(1, 0), cA + kstep, voffA); PG8_STAGE(PG8_SB(1, 1), cB + hstep + kstep, voffB);
;     PG8_WAIT_V(6); PG8_BAR;
;     for (;;) {
;         const bool has_next = S.next(ui + 1, nxt);
;         const char* nA = has_next ? (const char*)g.A + (size_t)nxt.pm * tstep : cA; const char* nB = has_next ? (const char*)g.Bt + (size_t)nxt.pn * tstep : cB;
.LBB0_2383:
	s_waitcnt lgkmcnt(0)
	s_add_u32 s14, s14, 0x29bb8000
	s_addc_u32 s15, s15, 0
	s_lshl_b32 s11, s8, 6
	s_lshl_b32 s18, s8, 13
	s_lshl_b32 s8, s9, 5
	s_mov_b64 s[16:17], 0x80
	s_and_b32 s77, s8, 0x60
	s_add_i32 m0, s73, 0x18000
	v_lshl_add_u64 v[6:7], v[6:7], 0, s[16:17]
	s_lshl_b32 s19, s77, 7
	s_waitcnt vmcnt(4)
	s_barrier
	global_load_lds_dwordx4 v[6:7], off
	v_lshl_add_u64 v[4:5], v[4:5], 0, s[16:17]
	s_add_i32 m0, s73, 0x1a000
	s_add_i32 s78, s73, 0x8000
	s_add_i32 s79, s73, 0xa000
	global_load_lds_dwordx4 v[4:5], off
	v_lshl_add_u64 v[2:3], v[2:3], 0, s[16:17]
	s_mov_b32 m0, s78
	s_add_u32 s8, s62, 0x10080
	global_load_lds_dwordx4 v[2:3], off
	v_lshl_add_u64 v[0:1], v[0:1], 0, s[16:17]
	s_mov_b32 m0, s79
	s_addc_u32 s9, s63, 0
	global_load_lds_dwordx4 v[0:1], off
	s_add_i32 m0, s73, 0x1c000
	v_lshl_add_u64 v[0:1], s[8:9], 0, v[130:131]
	global_load_lds_dwordx4 v[0:1], off
	v_lshl_add_u64 v[0:1], s[8:9], 0, v[134:135]
	s_add_i32 m0, s73, 0x1e000
	v_lshlrev_b32_e32 v2, 2, v8
	global_load_lds_dwordx4 v[0:1], off
	v_lshrrev_b32_e32 v1, 1, v8
	v_and_b32_e32 v144, 24, v1
	v_and_b32_e32 v0, 15, v8
	v_lshlrev_b32_e32 v1, 1, v144
	v_lshl_or_b32 v1, v0, 6, v1
	v_and_b32_e32 v2, 32, v2
	s_waitcnt vmcnt(6)
	v_bitop3_b32 v3, v1, s18, v2 bitop3:0xde
	v_bitop3_b32 v145, v1, s19, v2 bitop3:0xde
	s_ashr_i32 s8, s11, 31
	s_add_i32 s81, 0, 0x10000
	s_add_i32 s84, 0, 0x14000
	v_or_b32_e32 v136, s11, v0
	v_mov_b32_e32 v137, s8
	s_add_i32 s80, s100, s44
	v_mov_b64_e32 v[140:141], 0x142
	v_add_u32_e32 v146, s81, v145
	v_add_u32_e32 v147, 0, v3
	s_add_i32 s82, s73, 0xc000
	s_add_i32 s83, s73, 0xe000
	v_add_u32_e32 v148, s84, v145
	s_mov_b64 s[18:19], 0x100
	s_mov_b64 s[24:25], 0x180
	s_movk_i32 s85, 0x100
	s_movk_i32 s86, 0x300
	s_mov_b64 s[26:27], 0x90
	s_mov_b64 s[28:29], 0xa0
	s_mov_b64 s[30:31], 0xb0
	s_mov_b64 s[46:47], s[100:101]
	s_barrier
	s_branch .LBB0_2385

;     DI bool next(int i, Unit& u) const {
;         const long L = (long)i * G + c; if (L >= nwg) return false;
;         int wgid = (int)L; { const int q = nwg / NXCD, r = nwg % NXCD, xcd = wgid % NXCD, off = wgid / NXCD; wgid = (xcd < r ? xcd * (q + 1) : r * (q + 1) + (xcd - r) * q) + off; }
;         const int nig = WGM * nN, gid = wgid / nig, fm = gid * WGM, gsz = (nM - fm) < WGM ? (nM - fm) : WGM;
;         u.pm = fm + ((wgid % nig) % gsz); u.pn = (wgid % nig) / gsz; return true;
;     }
.LBB0_2426:
	v_mov_b32_e32 v8, v254
	s_and_b64 vcc, exec, s[4:5]
	v_add_u32_e32 v0, s33, v8
	s_nop 0
	v_readfirstlane_b32 s71, v0
	s_cbranch_vccnz .LBB0_2432
	s_lshr_b32 s8, s3, 29
	s_add_u32 s100, s2, 224
	s_and_b32 s100, s100, 0xff
	s_mov_b32 s101, 0
	s_add_i32 s10, s100, s8
	s_and_b32 s8, s10, -8
	s_sub_i32 s11, s100, s8
	s_cmp_gt_i32 s11, 2
	s_cbranch_scc0 .LBB0_2429
	s_mul_i32 s8, s11, 40
	s_or_b32 s16, s8, 3
	s_cbranch_execz .LBB0_2430
	s_branch .LBB0_2431

;     DI bool next(int i, Unit& u) const {
;         const long L = (long)i * G + c; if (L >= nwg) return false;
;         int wgid = (int)L; { const int q = nwg / NXCD, r = nwg % NXCD, xcd = wgid % NXCD, off = wgid / NXCD; wgid = (xcd < r ? xcd * (q + 1) : r * (q + 1) + (xcd - r) * q) + off; }
;         const int nig = WGM * nN, gid = wgid / nig, fm = gid * WGM, gsz = (nM - fm) < WGM ? (nM - fm) : WGM;
;         u.pm = fm + ((wgid % nig) % gsz); u.pn = (wgid % nig) / gsz; return true;
;     }
; template <class Epi>
; DI void gemm_phase(int wv, LAS unsigned char* lds, const Gemm g, const StaticOrder& S, const Epi& E) {
;     ...
;         const bool has_next = S.next(ui + 1, nxt);
;         const char* nA = has_next ? (const char*)g.A + (size_t)nxt.pm * tstep : cA; const char* nB = has_next ? (const char*)g.Bt + (size_t)nxt.pn * tstep : cB;
.LBB0_2437:
	s_add_i32 s79, s79, 1
	s_mul_i32 s4, s79, s45
	s_mul_hi_u32 s5, s79, s44
	s_add_i32 s5, s5, s4
	s_mul_i32 s4, s79, s44
	s_add_u32 s30, s4, s100
	s_addc_u32 s31, s5, s3
	v_cmp_gt_i64_e64 s[4:5], s[30:31], v[140:141]
	s_and_b64 vcc, exec, s[4:5]
	s_cbranch_vccnz .LBB0_2443
	s_ashr_i32 s9, s30, 31
	s_lshr_b32 s9, s9, 29
	s_add_i32 s9, s30, s9
	s_and_b32 s26, s9, -8
	s_sub_i32 s28, s30, s26
	s_cmp_gt_i32 s28, 2
	s_mov_b64 s[26:27], -1
	s_cbranch_scc0 .LBB0_2440
	s_mul_i32 s26, s28, 40
	s_or_b32 s29, s26, 3
	s_mov_b64 s[26:27], 0
